# t23 + XCD leader waits for its L2 invalidate to complete before releasing the other workgroups
# baseline (speedup 1.0000x reference)
.LBB0_190:
	s_or_b64 exec, exec, s[6:7]
	s_mov_b64 s[6:7], exec
	v_mbcnt_lo_u32_b32 v1, s6, 0
	v_mbcnt_hi_u32_b32 v1, s7, v1
	v_cmp_eq_u32_e32 vcc, 0, v1
	s_waitcnt vmcnt(0)
	buffer_inv sc1
	s_waitcnt vmcnt(0)
	s_and_saveexec_b64 s[10:11], vcc
	s_cbranch_execz .LBB0_192
	s_bcnt1_i32_b64 s6, s[6:7]
	v_mov_b32_e32 v1, 0x2000
	v_mov_b32_e32 v2, s6
	global_atomic_add v1, v2, s[4:5] offset:1024

.LBB0_508:
	s_or_b64 exec, exec, s[6:7]
	s_mov_b64 s[6:7], exec
	v_mbcnt_lo_u32_b32 v0, s6, 0
	v_mbcnt_hi_u32_b32 v0, s7, v0
	v_cmp_eq_u32_e32 vcc, 0, v0
	s_waitcnt vmcnt(0)
	buffer_inv sc1
	s_waitcnt vmcnt(0)
	s_and_saveexec_b64 s[8:9], vcc
	s_cbranch_execz .LBB0_510
	s_bcnt1_i32_b64 s6, s[6:7]
	v_mov_b32_e32 v0, 0x2000
	v_mov_b32_e32 v1, s6
	global_atomic_add v0, v1, s[4:5] offset:1024

.LBB0_745:
	s_or_b64 exec, exec, s[8:9]
	s_mov_b64 s[8:9], exec
	v_mbcnt_lo_u32_b32 v0, s8, 0
	v_mbcnt_hi_u32_b32 v0, s9, v0
	v_cmp_eq_u32_e32 vcc, 0, v0
	s_waitcnt vmcnt(0)
	buffer_inv sc1
	s_waitcnt vmcnt(0)
	s_and_saveexec_b64 s[10:11], vcc
	s_cbranch_execz .LBB0_747
	s_bcnt1_i32_b64 s8, s[8:9]
	v_mov_b32_e32 v0, 0x2000
	v_mov_b32_e32 v1, s8
	global_atomic_add v0, v1, s[6:7] offset:1024
